# plus sample recurrence prologue: the three history loads of a token-conv task issued together and waited once
# speedup vs baseline: 1.0314x; 1.0004x over previous
; #define LAS __attribute__((address_space(3)))
; __device__ __forceinline__ float bf2f(bf16_t b) { return __uint_as_float(((unsigned)b) << 16); }
; __device__ __forceinline__ float silu_f(float x) { return x * __builtin_amdgcn_rcpf(1.0f + __expf(-x)); }
; __device__ __forceinline__ void gdn_sample_item(LAS unsigned char* lds, int item, const bf16_t* qkv, const float* bg, const float* gconv_w, const float* st_gconv, const float* st_grec, bf16_t* zb, const float* gnorm_w, float* srec) {
;     ...
;     for (int task = tid; task < 768; task += NTHREADS) { const int ch = task % 384, half = task / 384, part = ch >> 7, colq = part * 1024 + h * 128 + (ch & 127);
;         LAS float* dst = (part == 0 ? qs : part == 1 ? ks : vs) + (ch & 127);
;         const float w0 = gconv_w[colq], w1 = gconv_w[CONVCH + colq], w2 = gconv_w[2 * CONVCH + colq], w3 = gconv_w[3 * CONVCH + colq];
;         const int tb = 4 * half; float xm[3];
; #pragma unroll
;         for (int j = 0; j < 3; ++j) { const int tt = tb - 3 + j; xm[j] = tt >= 0 ? bf2f(qkv[(size_t)(rowbase + tt) * CONVCH + colq]) : st_gconv[((size_t)sb * 3 + (3 + tt)) * CONVCH + colq]; }
; #pragma unroll
;         for (int i = 0; i < 4; ++i) { const float xc = bf2f(qkv[(size_t)(rowbase + tb + i) * CONVCH + colq]);
;             const float y = w0 * xm[0] + w1 * xm[1] + w2 * xm[2] + w3 * xc; xm[0] = xm[1]; xm[1] = xm[2]; xm[2] = xc; dst[(tb + i) * 128] = silu_f(y); } }
.LBB0_711:
	s_mov_b32 s20, 0x2aaaaaab
	v_mul_hi_i32 v2, v12, s20
	v_lshrrev_b32_e32 v3, 31, v2
	v_ashrrev_i32_e32 v2, 6, v2
	v_add_u32_e32 v14, v2, v3
	v_mul_i32_i24_e32 v2, 0x180, v14
	v_sub_u32_e32 v10, v12, v2
	v_ashrrev_i32_e32 v16, 7, v10
	v_lshlrev_b32_e32 v2, 10, v16
	v_and_b32_e32 v15, 0x7f, v10
	v_or3_b32 v2, v2, s0, v15
	v_ashrrev_i32_e32 v3, 31, v2
	v_lshlrev_b64 v[6:7], 2, v[2:3]
	v_lshl_add_u64 v[4:5], s[72:73], 0, v[6:7]
	v_add_co_u32_e32 v36, vcc, s26, v4
	global_load_dword v8, v[4:5], off
	s_nop 0
	v_addc_co_u32_e32 v37, vcc, 0, v5, vcc
	global_load_dword v9, v[36:37], off
	v_add_co_u32_e32 v36, vcc, 0x6000, v4
	v_readlane_b32 s40, v245, 3
	s_nop 0
	v_addc_co_u32_e32 v37, vcc, 0, v5, vcc
	v_add_co_u32_e32 v4, vcc, 0x9000, v4
	global_load_dword v11, v[36:37], off
	s_nop 0
	v_addc_co_u32_e32 v5, vcc, 0, v5, vcc
	global_load_dword v13, v[4:5], off
	v_readlane_b32 s44, v245, 7
	v_readlane_b32 s45, v245, 8
	s_movk_i32 s20, 0x180
	v_lshlrev_b32_e32 v4, 2, v14
	v_lshl_add_u64 v[6:7], s[44:45], 0, v[6:7]
	v_cmp_gt_i32_e32 vcc, s20, v12
	v_readlane_b32 s41, v245, 4
	v_readlane_b32 s42, v245, 5
	v_readlane_b32 s43, v245, 6
	v_readlane_b32 s46, v245, 9
	v_readlane_b32 s47, v245, 10
	v_readlane_b32 s48, v245, 11
	v_readlane_b32 s49, v245, 12
	v_readlane_b32 s50, v245, 13
	v_readlane_b32 s51, v245, 14
	v_readlane_b32 s52, v245, 15
	v_readlane_b32 s53, v245, 16
	v_readlane_b32 s54, v245, 17
	v_readlane_b32 s55, v245, 18
	v_lshl_add_u64 v[2:3], v[2:3], 1, s[88:89]
	s_and_saveexec_b64 s[20:21], vcc
	s_xor_b64 s[20:21], exec, s[20:21]
	s_cbranch_execz .Lsp_else
	v_ashrrev_i32_e32 v5, 31, v4
	v_lshl_add_u64 v[36:37], s[8:9], 0, v[4:5]
	v_mad_u64_u32 v[38:39], s[38:39], v36, s26, v[6:7]
	v_mov_b32_e32 v36, v39
	v_mad_u64_u32 v[36:37], s[38:39], v37, s26, v[36:37]
	v_mov_b32_e32 v39, v36
	global_load_dword v5, v[38:39], off
	v_or_b32_e32 v36, 1, v4
	v_ashrrev_i32_e32 v37, 31, v36
	v_lshl_add_u64 v[36:37], s[8:9], 0, v[36:37]
	v_mad_u64_u32 v[38:39], s[38:39], v36, s26, v[6:7]
	v_mov_b32_e32 v36, v39
	v_mad_u64_u32 v[36:37], s[38:39], v37, s26, v[36:37]
	v_mov_b32_e32 v39, v36
	global_load_dword v17, v[38:39], off
	v_or_b32_e32 v36, 2, v4
	v_ashrrev_i32_e32 v37, 31, v36
	v_lshl_add_u64 v[36:37], s[8:9], 0, v[36:37]
	v_mad_u64_u32 v[38:39], s[38:39], v36, s26, v[6:7]
	v_mov_b32_e32 v36, v39
	v_mad_u64_u32 v[36:37], s[38:39], v37, s26, v[36:37]
	v_mov_b32_e32 v39, v36
	global_load_dword v36, v[38:39], off
.Lsp_else:
	s_or_saveexec_b64 s[20:21], s[20:21]
	s_xor_b64 exec, exec, s[20:21]
	s_cbranch_execz .LBB0_710
	v_add_u32_e32 v40, s35, v4
	v_mad_i64_i32 v[40:41], s[38:39], v40, s27, v[2:3]
	global_load_ushort v5, v[40:41], off
	v_add_u32_e32 v40, s36, v4
	v_mad_i64_i32 v[40:41], s[38:39], v40, s27, v[2:3]
	global_load_ushort v17, v[40:41], off
	v_add_u32_e32 v40, s37, v4
	v_mad_i64_i32 v[40:41], s[38:39], v40, s27, v[2:3]
	global_load_ushort v36, v[40:41], off
	s_waitcnt vmcnt(0)
	v_lshlrev_b32_e32 v5, 16, v5
	v_lshlrev_b32_e32 v17, 16, v17
	v_lshlrev_b32_e32 v36, 16, v36
	s_branch .LBB0_710
